# union: stacked version + EpiRes epilogues de-serialised + mLSTM normalisation all-reduces via permlane swaps
# speedup vs baseline: 1.0033x; 1.0033x over previous
.LBB0_442:
	s_waitcnt lgkmcnt(0)
	s_barrier
	ds_read_b128 v[92:95], v179 offset:34816
	ds_read_b128 v[96:99], v200
	ds_read_b128 v[88:91], v178
	s_waitcnt lgkmcnt(0)
	ds_read_b128 v[84:87], v178 offset:192
	ds_read_b128 v[146:149], v200 offset:64
	ds_read_b128 v[104:107], v179 offset:34880
	ds_read_b32 v145, v176
	v_mfma_f32_16x16x32_bf16 v[100:103], v[92:95], v[96:99], 0
	ds_read_b128 v[108:111], v179 offset:34944
	ds_read_b128 v[154:157], v200 offset:128
	ds_read_b128 v[112:115], v179 offset:35008
	ds_read_b128 v[230:233], v200 offset:192
	v_or_b32_e32 v158, v212, v171
	v_mfma_f32_16x16x32_bf16 v[150:153], v[88:91], v[96:99], 0
	v_lshlrev_b32_e32 v228, 2, v158
	ds_read2st64_b32 v[158:159], v180 offset0:2 offset1:3
	v_add_u32_e32 v207, 0xd000, v181
	s_waitcnt lgkmcnt(0)
	v_mfma_f32_16x16x32_bf16 v[96:99], v[104:107], v[146:149], v[100:103]
	v_add_f32_e32 v145, 0, v145
	v_cmp_lt_i32_e32 vcc, v218, v213
	v_mfma_f32_16x16x32_bf16 v[100:103], v[108:111], v[154:157], v[96:99]
	v_mfma_f32_16x16x32_bf16 v[234:237], v[112:115], v[230:233], v[100:103]
	s_nop 3
	ds_read_b128 v[96:99], v178 offset:64
	s_nop 1
	ds_read_b128 v[100:103], v178 offset:128
	s_waitcnt lgkmcnt(0)
	v_mfma_f32_16x16x32_bf16 v[146:149], v[96:99], v[146:149], v[150:153]
	ds_bpermute_b32 v166, v228, v234
	s_nop 1
	v_cndmask_b32_e32 v150, v211, v218, vcc
	v_lshlrev_b32_e32 v205, 2, v150
	v_mfma_f32_16x16x32_bf16 v[146:149], v[100:103], v[154:157], v[146:149]
	ds_read2_b64 v[154:157], v207 offset1:4
	s_waitcnt lgkmcnt(0)
	v_fmac_f32_e32 v145, v158, v166
	v_max_f32_e32 v166, v159, v159
	v_max_f32_e64 v145, |v145|, v166
	ds_read2st64_b64 v[150:153], v175 offset1:1
	v_mfma_f32_16x16x32_bf16 v[146:149], v[84:87], v[230:233], v[146:149]
	v_div_scale_f32 v166, s[0:1], v145, v145, 1.0
	v_rcp_f32_e32 v167, v166
	s_nop 5
	v_pk_mul_f32 v[148:149], v[158:159], v[148:149] op_sel_hi:[0,1]
	v_pk_mul_f32 v[146:147], v[158:159], v[146:147] op_sel_hi:[0,1]
	s_waitcnt lgkmcnt(0)
	s_nop 0
	v_mfma_f32_16x16x32_bf16 v[146:149], v[154:157], v[150:153], v[146:149]
	v_fma_f32 v150, -v166, v167, 1.0
	v_fmac_f32_e32 v167, v150, v167
	v_div_scale_f32 v150, vcc, 1.0, v145, 1.0
	v_mul_f32_e32 v151, v150, v167
	v_fma_f32 v152, -v166, v151, v150
	v_fmac_f32_e32 v151, v152, v167
	v_fma_f32 v150, -v166, v151, v150
	v_div_fmas_f32 v150, v150, v167, v151
	v_div_fixup_f32 v150, v150, v145, 1.0
	v_pk_mul_f32 v[154:155], v[150:151], v[146:147] op_sel_hi:[0,1]
	v_pk_mul_f32 v[152:153], v[150:151], v[148:149] op_sel_hi:[0,1]
	v_mov_b32_e32 v148, v152
	v_mov_b32_e32 v149, v154
	v_pk_mul_f32 v[148:149], v[148:149], v[148:149]
	v_add_f32_e32 v145, 0, v154
	v_pk_fma_f32 v[150:151], v[154:155], v[154:155], v[148:149]
	v_add_f32_e32 v145, v155, v145
	v_pk_add_f32 v[148:149], v[148:149], v[150:151] op_sel_hi:[0,1]
	v_pk_mul_f32 v[150:151], v[152:153], v[152:153]
	v_add_f32_e32 v146, v152, v145
	v_mov_b32_e32 v148, v153
	v_mov_b32_e32 v147, v151
	v_pk_add_f32 v[146:147], v[148:149], v[146:147]
	v_mov_b32_e32 v148, v146
	v_mov_b32_e32 v149, v147
	s_nop 1
	v_permlane16_swap_b32_e32 v148, v146
	v_permlane16_swap_b32_e32 v149, v147
	v_cmp_lt_i32_e32 vcc, v144, v213
	s_nop 1
	v_cndmask_b32_e32 v144, v211, v144, vcc
	v_lshlrev_b32_e32 v206, 2, v144
	s_waitcnt lgkmcnt(0)
	v_pk_add_f32 v[144:145], v[146:147], v[148:149]
	v_mov_b32_e32 v146, v144
	v_mov_b32_e32 v147, v145
	s_nop 1
	v_permlane32_swap_b32_e32 v146, v144
	v_permlane32_swap_b32_e32 v147, v145
	s_and_saveexec_b64 s[0:1], s[4:5]
	s_cbranch_execz .LBB0_444
	s_waitcnt lgkmcnt(0)
	v_pk_add_f32 v[144:145], v[144:145], v[146:147]
	v_add_u32_e32 v146, 0, v187
	v_add_u32_e32 v146, 0x1b100, v146
	ds_write_b64 v146, v[144:145]
.LBB0_444:
	s_or_b64 exec, exec, s[0:1]
	s_waitcnt lgkmcnt(0)
	ds_read_b128 v[144:147], v203
	ds_read_b128 v[148:151], v203 offset:64
	ds_read_b128 v[230:233], v203 offset:128
	ds_read_b128 v[234:237], v203 offset:192
	s_waitcnt lgkmcnt(0)
	v_mfma_f32_16x16x32_bf16 v[156:159], v[92:95], v[144:147], 0
	v_mfma_f32_16x16x32_bf16 v[156:159], v[104:107], v[148:151], v[156:159]
	v_mfma_f32_16x16x32_bf16 v[156:159], v[108:111], v[230:233], v[156:159]
	v_mfma_f32_16x16x32_bf16 v[144:147], v[88:91], v[144:147], 0
	v_mfma_f32_16x16x32_bf16 v[156:159], v[112:115], v[234:237], v[156:159]
	v_mfma_f32_16x16x32_bf16 v[144:147], v[96:99], v[148:151], v[144:147]
	ds_read2_b32 v[148:149], v176 offset0:64 offset1:80
	s_nop 5
	ds_read2_b32 v[158:159], v180 offset0:144 offset1:208
	ds_bpermute_b32 v156, v228, v156
	s_waitcnt lgkmcnt(0)
	v_add_f32_e32 v148, 0, v148
	v_mfma_f32_16x16x32_bf16 v[144:147], v[100:103], v[230:233], v[144:147]
	v_add_f32_e32 v157, v148, v149
	ds_read2_b64 v[148:151], v207 offset1:4
	v_fmac_f32_e32 v157, v158, v156
	v_mfma_f32_16x16x32_bf16 v[144:147], v[84:87], v[234:237], v[144:147]
	v_max_f32_e32 v156, v159, v159
	v_max_f32_e64 v166, |v157|, v156
	v_div_scale_f32 v167, s[0:1], v166, v166, 1.0
	v_rcp_f32_e32 v168, v167
	s_nop 3
	v_pk_mul_f32 v[146:147], v[158:159], v[146:147] op_sel_hi:[0,1]
	v_pk_mul_f32 v[144:145], v[158:159], v[144:145] op_sel_hi:[0,1]
	ds_read2st64_b64 v[156:159], v175 offset0:4 offset1:5
	v_fma_f32 v229, -v167, v168, 1.0
	v_div_scale_f32 v169, vcc, 1.0, v166, 1.0
	v_fmac_f32_e32 v168, v229, v168
	s_waitcnt lgkmcnt(0)
	v_mfma_f32_16x16x32_bf16 v[144:147], v[148:151], v[156:159], v[144:147]
	v_mul_f32_e32 v148, v169, v168
	v_fma_f32 v149, -v167, v148, v169
	v_fmac_f32_e32 v148, v149, v168
	v_fma_f32 v149, -v167, v148, v169
	v_div_fmas_f32 v148, v149, v168, v148
	v_div_fixup_f32 v148, v148, v166, 1.0
	s_nop 1
	v_pk_mul_f32 v[150:151], v[148:149], v[144:145] op_sel_hi:[0,1]
	v_add_f32_e32 v145, 0, v150
	v_pk_mul_f32 v[148:149], v[148:149], v[146:147] op_sel_hi:[0,1]
	v_add_f32_e32 v145, v151, v145
	v_mov_b32_e32 v144, v148
	v_add_f32_e32 v146, v148, v145
	v_mov_b32_e32 v145, v150
	v_pk_mul_f32 v[144:145], v[144:145], v[144:145]
	s_nop 0
	v_pk_fma_f32 v[156:157], v[150:151], v[150:151], v[144:145]
	s_nop 0
	v_pk_add_f32 v[144:145], v[144:145], v[156:157] op_sel_hi:[0,1]
	v_pk_mul_f32 v[156:157], v[148:149], v[148:149]
	v_mov_b32_e32 v144, v149
	v_mov_b32_e32 v147, v157
	v_pk_add_f32 v[144:145], v[144:145], v[146:147]
	v_mov_b32_e32 v146, v144
	v_mov_b32_e32 v147, v145
	s_nop 1
	v_permlane16_swap_b32_e32 v146, v144
	v_permlane16_swap_b32_e32 v147, v145
	s_waitcnt lgkmcnt(0)
	v_pk_add_f32 v[144:145], v[144:145], v[146:147]
	v_mov_b32_e32 v146, v144
	v_mov_b32_e32 v147, v145
	s_nop 1
	v_permlane32_swap_b32_e32 v146, v144
	v_permlane32_swap_b32_e32 v147, v145
	s_and_saveexec_b64 s[0:1], s[4:5]
	s_cbranch_execz .LBB0_446
	s_add_i32 s19, 0, 0x1b100
	s_waitcnt lgkmcnt(0)
	v_pk_add_f32 v[144:145], v[144:145], v[146:147]
	v_add_u32_e32 v146, s19, v187
	ds_write_b64 v146, v[144:145] offset:128
.LBB0_446:
	s_or_b64 exec, exec, s[0:1]
	s_waitcnt lgkmcnt(0)
	ds_read_b128 v[144:147], v203 offset:4352
	ds_read_b128 v[156:159], v203 offset:4416
	ds_read_b128 v[230:233], v203 offset:4480
	ds_read_b128 v[234:237], v203 offset:4544
	ds_read2_b32 v[166:167], v180 offset0:160 offset1:224
	s_waitcnt lgkmcnt(0)
	v_mfma_f32_16x16x32_bf16 v[238:241], v[92:95], v[144:147], 0
	ds_read2_b32 v[168:169], v176 offset0:128 offset1:144
	s_waitcnt lgkmcnt(0)
	v_add_f32_e32 v168, 0, v168
	v_mfma_f32_16x16x32_bf16 v[144:147], v[88:91], v[144:147], 0
	v_add_f32_e32 v168, v168, v169
	ds_read_b32 v169, v176 offset:640
	s_waitcnt lgkmcnt(0)
	v_add_f32_e32 v168, v168, v169
	v_mfma_f32_16x16x32_bf16 v[144:147], v[96:99], v[156:159], v[144:147]
	v_mfma_f32_16x16x32_bf16 v[238:241], v[104:107], v[156:159], v[238:241]
	v_mfma_f32_16x16x32_bf16 v[144:147], v[100:103], v[230:233], v[144:147]
	v_mfma_f32_16x16x32_bf16 v[238:241], v[108:111], v[230:233], v[238:241]
	ds_read2st64_b64 v[156:159], v175 offset0:8 offset1:9
	ds_read2_b64 v[230:233], v207 offset1:4
	v_mfma_f32_16x16x32_bf16 v[144:147], v[84:87], v[234:237], v[144:147]
	v_mfma_f32_16x16x32_bf16 v[238:241], v[112:115], v[234:237], v[238:241]
	s_nop 6
	v_mul_f32_e64 v146, v166, v146
	v_mul_f32_e64 v147, v166, v147
	v_pk_mul_f32 v[144:145], v[166:167], v[144:145] op_sel_hi:[0,1]
	ds_bpermute_b32 v229, v228, v238
	s_waitcnt lgkmcnt(0)
	v_fmac_f32_e32 v168, v166, v229
	v_mfma_f32_16x16x32_bf16 v[144:147], v[230:233], v[156:159], v[144:147]
	ds_read2st64_b64 v[156:159], v175 offset0:10 offset1:11
	ds_read2_b64 v[230:233], v207 offset0:8 offset1:12
	s_waitcnt lgkmcnt(0)
	v_mfma_f32_16x16x32_bf16 v[156:159], v[230:233], v[156:159], v[144:147]
	s_nop 3
	v_max_f32_e32 v144, v167, v167
	v_max_f32_e64 v144, |v168|, v144
	v_div_scale_f32 v145, s[0:1], v144, v144, 1.0
	v_rcp_f32_e32 v146, v145
	s_nop 0
	v_fma_f32 v147, -v145, v146, 1.0
	v_fmac_f32_e32 v146, v147, v146
	v_div_scale_f32 v147, vcc, 1.0, v144, 1.0
	v_mul_f32_e32 v166, v147, v146
	v_fma_f32 v167, -v145, v166, v147
	v_fmac_f32_e32 v166, v167, v146
	v_fma_f32 v145, -v145, v166, v147
	v_div_fmas_f32 v145, v145, v146, v166
	v_div_fixup_f32 v144, v145, v144, 1.0
	v_pk_mul_f32 v[146:147], v[144:145], v[156:157] op_sel_hi:[0,1]
	v_add_f32_e32 v145, 0, v146
	v_add_f32_e32 v156, v147, v145
	v_pk_mul_f32 v[144:145], v[144:145], v[158:159] op_sel_hi:[0,1]
	v_mov_b32_e32 v158, v144
	v_mov_b32_e32 v159, v146
	v_pk_mul_f32 v[158:159], v[158:159], v[158:159]
	v_add_f32_e32 v156, v144, v156
	v_pk_fma_f32 v[166:167], v[146:147], v[146:147], v[158:159]
	s_nop 0
	v_pk_add_f32 v[158:159], v[158:159], v[166:167] op_sel_hi:[0,1]
	v_pk_mul_f32 v[166:167], v[144:145], v[144:145]
	v_mov_b32_e32 v158, v145
	v_mov_b32_e32 v157, v167
	v_pk_add_f32 v[156:157], v[158:159], v[156:157]
	v_mov_b32_e32 v158, v156
	v_mov_b32_e32 v159, v157
	s_nop 1
	v_permlane16_swap_b32_e32 v158, v156
	v_permlane16_swap_b32_e32 v159, v157
	s_waitcnt lgkmcnt(0)
	v_pk_add_f32 v[156:157], v[156:157], v[158:159]
	v_mov_b32_e32 v158, v156
	v_mov_b32_e32 v159, v157
	s_nop 1
	v_permlane32_swap_b32_e32 v158, v156
	v_permlane32_swap_b32_e32 v159, v157
	s_and_saveexec_b64 s[0:1], s[4:5]
	s_cbranch_execz .LBB0_448
	s_add_i32 s19, 0, 0x1b100
	s_waitcnt lgkmcnt(0)
	v_pk_add_f32 v[156:157], v[156:157], v[158:159]
	v_add_u32_e32 v158, s19, v187
	ds_write_b64 v158, v[156:157] offset:256
.LBB0_448:
	s_or_b64 exec, exec, s[0:1]
	s_waitcnt lgkmcnt(0)
	ds_read_b128 v[156:159], v203 offset:8704
	ds_read_b128 v[230:233], v203 offset:8768
	ds_read_b128 v[234:237], v203 offset:8832
	ds_read_b128 v[238:241], v203 offset:8896
	ds_read2_b32 v[166:167], v180 offset0:176 offset1:240
	s_waitcnt lgkmcnt(0)
	v_mfma_f32_16x16x32_bf16 v[92:95], v[92:95], v[156:159], 0
	v_mfma_f32_16x16x32_bf16 v[92:95], v[104:107], v[230:233], v[92:95]
	v_mfma_f32_16x16x32_bf16 v[92:95], v[108:111], v[234:237], v[92:95]
	v_mfma_f32_16x16x32_bf16 v[92:95], v[112:115], v[238:241], v[92:95]
	v_mfma_f32_16x16x32_bf16 v[88:91], v[88:91], v[156:159], 0
	v_mfma_f32_16x16x32_bf16 v[88:91], v[96:99], v[230:233], v[88:91]
	s_nop 5
	ds_bpermute_b32 v104, v228, v92
	ds_read2_b32 v[92:93], v176 offset0:192 offset1:208
	s_waitcnt lgkmcnt(0)
	v_add_f32_e32 v92, 0, v92
	v_add_f32_e32 v94, v92, v93
	ds_read2_b32 v[92:93], v176 offset0:224 offset1:240
	v_mfma_f32_16x16x32_bf16 v[88:91], v[100:103], v[234:237], v[88:91]
	s_waitcnt lgkmcnt(0)
	v_add_f32_e32 v92, v94, v92
	v_add_f32_e32 v105, v92, v93
	v_mfma_f32_16x16x32_bf16 v[84:87], v[84:87], v[238:241], v[88:91]
	s_nop 3
	ds_read2st64_b64 v[88:91], v175 offset0:12 offset1:13
	ds_read2_b64 v[92:95], v207 offset1:4
	v_fmac_f32_e32 v105, v166, v104
	s_nop 0
	v_pk_mul_f32 v[86:87], v[166:167], v[86:87] op_sel_hi:[0,1]
	v_pk_mul_f32 v[84:85], v[166:167], v[84:85] op_sel_hi:[0,1]
	s_waitcnt lgkmcnt(0)
	s_nop 0
	v_mfma_f32_16x16x32_bf16 v[84:87], v[92:95], v[88:91], v[84:87]
	ds_read2st64_b64 v[88:91], v175 offset0:14 offset1:15
	ds_read2_b64 v[92:95], v207 offset0:8 offset1:12
	s_waitcnt lgkmcnt(0)
	v_mfma_f32_16x16x32_bf16 v[86:89], v[92:95], v[88:91], v[84:87]
	s_nop 3
	v_max_f32_e32 v84, v167, v167
	v_max_f32_e64 v84, |v105|, v84
	v_div_scale_f32 v85, s[0:1], v84, v84, 1.0
	v_rcp_f32_e32 v90, v85
	s_nop 0
	v_fma_f32 v91, -v85, v90, 1.0
	v_fmac_f32_e32 v90, v91, v90
	v_div_scale_f32 v91, vcc, 1.0, v84, 1.0
	v_mul_f32_e32 v92, v91, v90
	v_fma_f32 v93, -v85, v92, v91
	v_fmac_f32_e32 v92, v93, v90
	v_fma_f32 v85, -v85, v92, v91
	v_div_fmas_f32 v85, v85, v90, v92
	v_div_fixup_f32 v84, v85, v84, 1.0
	v_pk_mul_f32 v[86:87], v[84:85], v[86:87] op_sel_hi:[0,1]
	v_add_f32_e32 v85, 0, v86
	v_add_f32_e32 v90, v87, v85
	v_pk_mul_f32 v[84:85], v[84:85], v[88:89] op_sel_hi:[0,1]
	v_add_f32_e32 v88, v84, v90
	v_mov_b32_e32 v90, v84
	v_mov_b32_e32 v91, v86
	v_pk_mul_f32 v[90:91], v[90:91], v[90:91]
	s_nop 0
	v_pk_fma_f32 v[92:93], v[86:87], v[86:87], v[90:91]
	s_nop 0
	v_pk_add_f32 v[90:91], v[90:91], v[92:93] op_sel_hi:[0,1]
	v_pk_mul_f32 v[92:93], v[84:85], v[84:85]
	v_mov_b32_e32 v90, v85
	v_mov_b32_e32 v89, v93
	v_pk_add_f32 v[88:89], v[90:91], v[88:89]
	v_mov_b32_e32 v90, v88
	v_mov_b32_e32 v91, v89
	s_nop 1
	v_permlane16_swap_b32_e32 v90, v88
	v_permlane16_swap_b32_e32 v91, v89
	s_waitcnt lgkmcnt(0)
	v_pk_add_f32 v[88:89], v[88:89], v[90:91]
	v_mov_b32_e32 v90, v88
	v_mov_b32_e32 v91, v89
	s_nop 1
	v_permlane32_swap_b32_e32 v90, v88
	v_permlane32_swap_b32_e32 v91, v89
	s_and_saveexec_b64 s[0:1], s[4:5]
	s_cbranch_execz .LBB0_450
	s_add_i32 s19, 0, 0x1b100
	s_waitcnt lgkmcnt(0)
	v_pk_add_f32 v[88:89], v[88:89], v[90:91]
	v_add_u32_e32 v90, s19, v187
	ds_write_b64 v90, v[88:89] offset:384
